# 8 bytes of never-executed padding ahead of the GEMM main loop (loop head at 56 mod 64; code-placement test)
# speedup vs baseline: 1.0009x; 1.0009x over previous
;     DI bool next(int i, Unit& u) const {
;     ...
;         if ((nM & (WGM - 1)) == 0) {
;             const int t = wgid >> 3, gid = (int)(((float)t + 0.5f) * invN);
;             u.pm = gid * WGM + (wgid & (WGM - 1)); u.pn = t - gid * nN; return true; }
;         const int nig = WGM * nN, gid = wgid / nig, fm = gid * WGM, gsz = (nM - fm) < WGM ? (nM - fm) : WGM;
;         u.pm = fm + ((wgid % nig) % gsz); u.pn = (wgid % nig) / gsz; return true;
.LBB0_785:
	s_abs_i32 s1, s3
	s_mul_hi_u32 s4, s1, s93
	s_mul_i32 s5, s4, s92
	s_ashr_i32 s0, s3, 31
	s_sub_i32 s1, s1, s5
	s_xor_b32 s0, s0, s54
	s_add_i32 s5, s4, 1
	s_sub_i32 s26, s1, s92
	s_cmp_ge_u32 s1, s92
	s_cselect_b32 s4, s5, s4
	s_cselect_b32 s1, s26, s1
	s_add_i32 s5, s4, 1
	s_cmp_ge_u32 s1, s92
	s_cselect_b32 s1, s5, s4
	s_xor_b32 s1, s1, s0
	s_sub_i32 s0, s1, s0
	s_lshl_b32 s1, s0, 3
	s_sub_i32 s4, s89, s1
	s_min_i32 s4, s4, 8
	s_abs_i32 s5, s4
	v_cvt_f32_u32_e32 v2, s5
	s_sub_i32 s28, 0, s5
	s_mul_i32 s0, s0, s43
	s_sub_i32 s0, s3, s0
	v_rcp_iflag_f32_e32 v2, v2
	s_abs_i32 s27, s0
	s_xor_b32 s26, s0, s4
	s_ashr_i32 s26, s26, 31
	v_mul_f32_e32 v2, 0x4f7ffffe, v2
	v_cvt_u32_f32_e32 v2, v2
	s_nop 0
	v_readfirstlane_b32 s29, v2
	s_mul_i32 s28, s28, s29
	s_mul_hi_u32 s28, s29, s28
	s_add_i32 s29, s29, s28
	s_mul_hi_u32 s28, s27, s29
	s_mul_i32 s29, s28, s5
	s_sub_i32 s27, s27, s29
	s_add_i32 s29, s28, 1
	s_sub_i32 s33, s27, s5
	s_cmp_ge_u32 s27, s5
	s_cselect_b32 s28, s29, s28
	s_cselect_b32 s27, s33, s27
	s_add_i32 s29, s28, 1
	s_cmp_ge_u32 s27, s5
	s_cselect_b32 s5, s29, s28
	s_xor_b32 s5, s5, s26
	s_sub_i32 s62, s5, s26
	s_mul_i32 s4, s62, s4
	s_sub_i32 s0, s0, s4
	s_add_i32 s63, s0, s1
	s_cbranch_execnz .LBB0_787
	s_nop 0
	s_nop 0
.LBB0_786:
	s_ashr_i32 s0, s3, 3
	v_cvt_f32_i32_e32 v2, s0
	s_and_b32 s1, s3, 7
	v_add_f32_e32 v2, 0.5, v2
	v_mul_f32_e32 v2, v182, v2
	v_cvt_i32_f32_e32 v2, v2
	s_nop 0
	v_readfirstlane_b32 s3, v2
	s_lshl_b32 s4, s3, 3
	s_mul_i32 s3, s94, s3
	s_or_b32 s63, s4, s1
	s_sub_i32 s62, s0, s3
